# ph_shw (layer-1 vectors, w_out shadow): shift-vector staging by direct HBM->LDS loads, 34 in flight, one wait
# speedup vs baseline: 1.0069x; 1.0017x over previous
; DEVI void ph_shw(const int wv, const Params& p, int l, unsigned char* lds, int blk_lo) {
;     ...
;     for (int it = bx; it < 256; it += nbx) {
;         const int n0 = it * 16;
;         __syncthreads();
;         for (int e = tid; e < 17 * 1024; e += NTHREADS) { const int r = e >> 10, k = e & 1023; shv[e] = mod[(size_t)r * 6144 + 3072 + k]; }
;         __syncthreads();
.LBB0_1198:
	s_waitcnt vmcnt(0)
	s_barrier
	s_cmp_lg_u32 s100, 0
	s_mov_b32 s100, 1
	s_cbranch_scc1 .LBB0_1206
	v_lshlrev_b32_e32 v110, 2, v74
	v_readfirstlane_b32 s101, v101
	s_nop 3
	s_add_u32 s34, s38, 0x3000
	s_addc_u32 s35, s39, 0
	s_mov_b32 m0, s101
	s_nop 0
	global_load_lds_dword v110, s[34:35]
	s_addk_i32 m0, 0x800
	s_add_u32 s34, s34, 0x800
	s_addc_u32 s35, s35, 0
	global_load_lds_dword v110, s[34:35]
	s_addk_i32 m0, 0x800
	s_add_u32 s34, s34, 0x5800
	s_addc_u32 s35, s35, 0
	global_load_lds_dword v110, s[34:35]
	s_addk_i32 m0, 0x800
	s_add_u32 s34, s34, 0x800
	s_addc_u32 s35, s35, 0
	global_load_lds_dword v110, s[34:35]
	s_addk_i32 m0, 0x800
	s_add_u32 s34, s34, 0x5800
	s_addc_u32 s35, s35, 0
	global_load_lds_dword v110, s[34:35]
	s_addk_i32 m0, 0x800
	s_add_u32 s34, s34, 0x800
	s_addc_u32 s35, s35, 0
	global_load_lds_dword v110, s[34:35]
	s_addk_i32 m0, 0x800
	s_add_u32 s34, s34, 0x5800
	s_addc_u32 s35, s35, 0
	global_load_lds_dword v110, s[34:35]
	s_addk_i32 m0, 0x800
	s_add_u32 s34, s34, 0x800
	s_addc_u32 s35, s35, 0
	global_load_lds_dword v110, s[34:35]
	s_addk_i32 m0, 0x800
	s_add_u32 s34, s34, 0x5800
	s_addc_u32 s35, s35, 0
	global_load_lds_dword v110, s[34:35]
	s_addk_i32 m0, 0x800
	s_add_u32 s34, s34, 0x800
	s_addc_u32 s35, s35, 0
	global_load_lds_dword v110, s[34:35]
	s_addk_i32 m0, 0x800
	s_add_u32 s34, s34, 0x5800
	s_addc_u32 s35, s35, 0
	global_load_lds_dword v110, s[34:35]
	s_addk_i32 m0, 0x800
	s_add_u32 s34, s34, 0x800
	s_addc_u32 s35, s35, 0
	global_load_lds_dword v110, s[34:35]
	s_addk_i32 m0, 0x800
	s_add_u32 s34, s34, 0x5800
	s_addc_u32 s35, s35, 0
	global_load_lds_dword v110, s[34:35]
	s_addk_i32 m0, 0x800
	s_add_u32 s34, s34, 0x800
	s_addc_u32 s35, s35, 0
	global_load_lds_dword v110, s[34:35]
	s_addk_i32 m0, 0x800
	s_add_u32 s34, s34, 0x5800
	s_addc_u32 s35, s35, 0
	global_load_lds_dword v110, s[34:35]
	s_addk_i32 m0, 0x800
	s_add_u32 s34, s34, 0x800
	s_addc_u32 s35, s35, 0
	global_load_lds_dword v110, s[34:35]
	s_addk_i32 m0, 0x800
	s_add_u32 s34, s34, 0x5800
	s_addc_u32 s35, s35, 0
	global_load_lds_dword v110, s[34:35]
	s_addk_i32 m0, 0x800
	s_add_u32 s34, s34, 0x800
	s_addc_u32 s35, s35, 0
	global_load_lds_dword v110, s[34:35]
	s_addk_i32 m0, 0x800
	s_add_u32 s34, s34, 0x5800
	s_addc_u32 s35, s35, 0
	global_load_lds_dword v110, s[34:35]
	s_addk_i32 m0, 0x800
	s_add_u32 s34, s34, 0x800
	s_addc_u32 s35, s35, 0
	global_load_lds_dword v110, s[34:35]
	s_addk_i32 m0, 0x800
	s_add_u32 s34, s34, 0x5800
	s_addc_u32 s35, s35, 0
	global_load_lds_dword v110, s[34:35]
	s_addk_i32 m0, 0x800
	s_add_u32 s34, s34, 0x800
	s_addc_u32 s35, s35, 0
	global_load_lds_dword v110, s[34:35]
	s_addk_i32 m0, 0x800
	s_add_u32 s34, s34, 0x5800
	s_addc_u32 s35, s35, 0
	global_load_lds_dword v110, s[34:35]
	s_addk_i32 m0, 0x800
	s_add_u32 s34, s34, 0x800
	s_addc_u32 s35, s35, 0
	global_load_lds_dword v110, s[34:35]
	s_addk_i32 m0, 0x800
	s_add_u32 s34, s34, 0x5800
	s_addc_u32 s35, s35, 0
	global_load_lds_dword v110, s[34:35]
	s_addk_i32 m0, 0x800
	s_add_u32 s34, s34, 0x800
	s_addc_u32 s35, s35, 0
	global_load_lds_dword v110, s[34:35]
	s_addk_i32 m0, 0x800
	s_add_u32 s34, s34, 0x5800
	s_addc_u32 s35, s35, 0
	global_load_lds_dword v110, s[34:35]
	s_addk_i32 m0, 0x800
	s_add_u32 s34, s34, 0x800
	s_addc_u32 s35, s35, 0
	global_load_lds_dword v110, s[34:35]
	s_addk_i32 m0, 0x800
	s_add_u32 s34, s34, 0x5800
	s_addc_u32 s35, s35, 0
	global_load_lds_dword v110, s[34:35]
	s_addk_i32 m0, 0x800
	s_add_u32 s34, s34, 0x800
	s_addc_u32 s35, s35, 0
	global_load_lds_dword v110, s[34:35]
	s_addk_i32 m0, 0x800
	s_add_u32 s34, s34, 0x5800
	s_addc_u32 s35, s35, 0
	global_load_lds_dword v110, s[34:35]
	s_addk_i32 m0, 0x800
	s_add_u32 s34, s34, 0x800
	s_addc_u32 s35, s35, 0
	global_load_lds_dword v110, s[34:35]
	s_addk_i32 m0, 0x800
	s_add_u32 s34, s34, 0x5800
	s_addc_u32 s35, s35, 0
	global_load_lds_dword v110, s[34:35]
	s_addk_i32 m0, 0x800
	s_add_u32 s34, s34, 0x800
	s_addc_u32 s35, s35, 0
	global_load_lds_dword v110, s[34:35]
	s_waitcnt vmcnt(0)
